# mLSTM step: the six tail P.V MFMAs' LDS fragment reads issued together ahead of the dependent chain (counted lgkmcnt) instead of one exposed LDS round trip per MFMA
# baseline (speedup 1.0000x reference)
.LBB0_1723:
	s_waitcnt lgkmcnt(0)
	s_barrier
	s_waitcnt lgkmcnt(0)
	v_cndmask_b32_e64 v0, 0, 1, s[54:55]
	v_cmp_ne_u32_e64 s[10:11], 1, v0
	s_andn2_b64 vcc, exec, s[54:55]
	s_cbranch_vccnz .LBB0_1730
	v_or_b32_e32 v0, s39, v101
	v_mul_u32_u24_e32 v2, 0x90, v0
	v_lshlrev_b32_e32 v14, 4, v100
	v_add3_u32 v15, v2, v14, s56
	ds_read_b128 v[2:5], v15
	v_or_b32_e32 v108, s35, v101
	v_mad_u64_u32 v[106:107], s[16:17], v108, s68, v[14:15]
	ds_read_b128 v[6:9], v106
	ds_read_b128 v[10:13], v106 offset:32
	ds_read_b128 v[102:105], v15 offset:32
	v_mad_u32_u24 v0, v0, s69, v14
	s_andn2_b64 vcc, exec, s[18:19]
	s_waitcnt lgkmcnt(2)
	v_mfma_f32_32x32x16_bf16 v[32:47], v[2:5], v[6:9], 0
	ds_read_b128 v[2:5], v15 offset:64
	ds_read_b128 v[6:9], v106 offset:64
	s_waitcnt lgkmcnt(2)
	v_mfma_f32_32x32x16_bf16 v[32:47], v[102:105], v[10:13], v[32:47]
	ds_read_b128 v[10:13], v106 offset:96
	ds_read_b128 v[102:105], v15 offset:96
	s_waitcnt lgkmcnt(2)
	v_mfma_f32_32x32x16_bf16 v[32:47], v[2:5], v[6:9], v[32:47]
	v_mul_lo_u32 v2, v108, s69
	v_lshl_add_u32 v3, v108, 2, v94
	v_add3_u32 v2, v2, v14, s40
	ds_read_b32 v8, v3
	ds_read_b128 v[4:7], v0 offset:54272
	ds_read_b128 v[106:109], v0 offset:54304
	ds_read_b128 v[110:113], v2
	s_waitcnt lgkmcnt(4)
	v_mfma_f32_32x32x16_bf16 v[32:47], v[102:105], v[10:13], v[32:47]
	s_waitcnt lgkmcnt(3)
	s_nop 10
	v_pk_mul_f32 v[46:47], v[8:9], v[46:47] op_sel_hi:[0,1]
	v_pk_mul_f32 v[44:45], v[8:9], v[44:45] op_sel_hi:[0,1]
	v_pk_mul_f32 v[42:43], v[8:9], v[42:43] op_sel_hi:[0,1]
	v_pk_mul_f32 v[40:41], v[8:9], v[40:41] op_sel_hi:[0,1]
	v_pk_mul_f32 v[38:39], v[8:9], v[38:39] op_sel_hi:[0,1]
	v_pk_mul_f32 v[36:37], v[8:9], v[36:37] op_sel_hi:[0,1]
	v_pk_mul_f32 v[34:35], v[8:9], v[34:35] op_sel_hi:[0,1]
	v_pk_mul_f32 v[32:33], v[8:9], v[32:33] op_sel_hi:[0,1]
	ds_read_b128 v[8:11], v2 offset:32
	ds_read_b128 v[200:203], v0 offset:54336
	ds_read_b128 v[204:207], v2 offset:64
	ds_read_b128 v[208:211], v0 offset:54368
	ds_read_b128 v[212:215], v2 offset:96
	ds_read_b128 v[216:219], v0 offset:54400
	ds_read_b128 v[220:223], v2 offset:128
	ds_read_b128 v[224:227], v0 offset:54432
	ds_read_b128 v[228:231], v2 offset:160
	ds_read_b128 v[232:235], v0 offset:54464
	ds_read_b128 v[236:239], v2 offset:192
	ds_read_b128 v[240:243], v0 offset:54496
	ds_read_b128 v[244:247], v2 offset:224
	s_waitcnt lgkmcnt(13)
	v_mfma_f32_32x32x16_bf16 v[32:47], v[4:7], v[110:113], v[32:47]
	s_waitcnt lgkmcnt(12)
	v_mfma_f32_32x32x16_bf16 v[32:47], v[106:109], v[8:11], v[32:47]
	s_cbranch_vccz .LBB0_1731
	s_andn2_b64 vcc, exec, s[30:31]
	s_cbranch_vccz .LBB0_1732

.LBB0_1731:
	s_waitcnt lgkmcnt(10)
	v_mfma_f32_32x32x16_bf16 v[32:47], v[200:203], v[204:207], v[32:47]
	s_andn2_b64 vcc, exec, s[30:31]
	s_cbranch_vccnz .LBB0_1726
.LBB0_1732:
	s_waitcnt lgkmcnt(8)
	v_mfma_f32_32x32x16_bf16 v[32:47], v[208:211], v[212:215], v[32:47]
	s_andn2_b64 vcc, exec, s[20:21]
	s_cbranch_vccnz .LBB0_1727
.LBB0_1733:
	s_waitcnt lgkmcnt(6)
	v_mfma_f32_32x32x16_bf16 v[32:47], v[216:219], v[220:223], v[32:47]
	s_andn2_b64 vcc, exec, s[36:37]
	s_cbranch_vccnz .LBB0_1728
.LBB0_1734:
	s_waitcnt lgkmcnt(4)
	v_mfma_f32_32x32x16_bf16 v[32:47], v[224:227], v[228:231], v[32:47]
	s_andn2_b64 vcc, exec, s[42:43]
	s_cbranch_vccnz .LBB0_1729
.LBB0_1735:
	s_waitcnt lgkmcnt(2)
	v_mfma_f32_32x32x16_bf16 v[32:47], v[232:235], v[236:239], v[32:47]
	s_andn2_b64 vcc, exec, s[44:45]
	s_cbranch_vccnz .LBB0_1737
.LBB0_1736:
	s_waitcnt lgkmcnt(0)
	v_mfma_f32_32x32x16_bf16 v[32:47], v[240:243], v[244:247], v[32:47]
